# scan: next-step d partial formed as X - d*Y from an early copy of the next kk fragment (7 of 16 steps)
# baseline (speedup 1.0000x reference)
; DI void scan_block(float* ldsf, const u16* __restrict__ R, const u16* __restrict__ KP, const u16* __restrict__ KK, const u16* __restrict__ KKA,
;                    const u16* __restrict__ V, const float* __restrict__ Wd, float* __restrict__ Y, int blk, int wid_k) {
;     ...
;     const float* bp = ldsf + cur * 16 * 336;
;     float* yb = ybuf + cur * 256;
;     if (worker) {
;       typedef float f2 __attribute__((ext_vector_type(2)));
;       f2 Sa = {S0, S1}, Sb = {S2, S3};
;       float4 w4 = *(const float4*)(bp + ks * 4);
;       float4 kk4 = *(const float4*)(bp + 64 + ks * 4);
;       float4 ka4 = *(const float4*)(bp + 128 + ks * 4);
;       float4 kp4 = *(const float4*)(bp + 192 + ks * 4);
;       float4 r4 = *(const float4*)(bp + 256 + ks * 4);
;       float vv = bp[320 + rowl];
;       float yp = 0.f;
; #pragma unroll
;       for (int step = 0; step < 16; ++step) {
;         float4 w4n = w4, kk4n = kk4, ka4n = ka4, kp4n = kp4, r4n = r4; float vvn = vv;
;         if (step + 1 < 16) {
;           const float* sp = bp + (step + 1) * 336;
;           w4n = *(const float4*)(sp + ks * 4);
;           kk4n = *(const float4*)(sp + 64 + ks * 4);
;           ka4n = *(const float4*)(sp + 128 + ks * 4);
;           kp4n = *(const float4*)(sp + 192 + ks * 4);
;           r4n = *(const float4*)(sp + 256 + ks * 4);
;           vvn = sp[320 + rowl];
;         }
;         const f2 kka = {kk4.x, kk4.y}, kkb = {kk4.z, kk4.w}, wa = {w4.x, w4.y}, wb = {w4.z, w4.w};
;         const f2 kaa = {ka4.x, ka4.y}, kab = {ka4.z, ka4.w}, kpa = {kp4.x, kp4.y}, kpb = {kp4.z, kp4.w};
;         const f2 ra = {r4.x, r4.y}, rb = {r4.z, r4.w};
;         const f2 d2 = Sa * kka + Sb * kkb;
;         float d = d2.x + d2.y;
;         const f2 ta = Sa * wa + kpa * vv, tb = Sb * wb + kpb * vv;
;         d = dpp_add<0xB1>(d); yp = dpp_add<0xB1>(yp);
;         d = dpp_add<0x4E>(d); yp = dpp_add<0x4E>(yp);
;         d = dpp_add<0x141>(d); yp = dpp_add<0x141>(yp);
;         d = dpp_add<0x140>(d); yp = dpp_add<0x140>(yp);
;         if (step > 0) yreg = (ks == step - 1) ? yp : yreg;
;         Sa = ta - kaa * d; Sb = tb - kab * d;
;         const f2 y2 = Sa * ra + Sb * rb;
;         yp = y2.x + y2.y;
;         w4 = w4n; kk4 = kk4n; ka4 = ka4n; kp4 = kp4n; r4 = r4n; vv = vvn;
;       }
.LBB0_1288:
	s_and_b32 s66, s62, 1
	s_mul_i32 s63, s66, 0x5400
	s_add_i32 s67, s63, 0
	s_mul_i32 s63, s66, 0xffffb000
	s_add_i32 s63, s67, s63
	s_and_saveexec_b64 s[64:65], s[6:7]
	s_cbranch_execz .LBB0_1290
	s_lshl_b32 s63, s66, 14
	s_add_i32 s63, s63, 0x10000
	v_lshl_add_u32 v99, v69, 2, s63
	v_lshl_add_u32 v79, v70, 2, s67
	ds_read_b128 v[108:111], v79 offset:1600
	ds_read_b128 v[18:21], v79
	ds_read_b128 v[22:25], v79 offset:256
	ds_read_b128 v[26:29], v79 offset:512
	ds_read_b128 v[30:33], v79 offset:768
	ds_read_b128 v[34:37], v79 offset:1024
	v_add_u32_e32 v78, s67, v76
	s_waitcnt lgkmcnt(3)
	v_pk_mul_f32 v[22:23], v[14:15], v[22:23]
	ds_read_b32 v68, v78 offset:1280
	ds_read_b128 v[38:41], v79 offset:1344
	ds_read_b128 v[42:45], v79 offset:1600
	ds_read_b128 v[46:49], v79 offset:1856
	ds_read_b128 v[50:53], v79 offset:2112
	ds_read_b128 v[64:67], v79 offset:2368
	ds_read_b32 v80, v78 offset:2624
	v_pk_fma_f32 v[22:23], v[16:17], v[24:25], v[22:23]
	s_nop 0
	v_add_f32_e32 v24, v22, v23
	s_waitcnt lgkmcnt(6)
	v_pk_mul_f32 v[22:23], v[30:31], v[68:69] op_sel_hi:[1,0]
	s_nop 0
	v_pk_fma_f32 v[14:15], v[14:15], v[18:19], v[22:23]
	v_pk_mul_f32 v[18:19], v[32:33], v[68:69] op_sel_hi:[1,0]
	s_nop 0
	v_pk_fma_f32 v[16:17], v[16:17], v[20:21], v[18:19]
	v_add_f32_dpp v18, v24, v24 quad_perm:[1,0,3,2] row_mask:0xf bank_mask:0xf bound_ctrl:1
	s_waitcnt lgkmcnt(12)
	v_pk_mul_f32 v[104:105], v[108:109], v[26:27]
	v_pk_mul_f32 v[102:103], v[108:109], v[14:15]
	v_add_f32_dpp v18, v18, v18 quad_perm:[2,3,0,1] row_mask:0xf bank_mask:0xf bound_ctrl:1
	v_pk_fma_f32 v[104:105], v[110:111], v[28:29], v[104:105]
	v_pk_fma_f32 v[102:103], v[110:111], v[16:17], v[102:103]
	v_add_f32_dpp v18, v18, v18 row_half_mirror row_mask:0xf bank_mask:0xf bound_ctrl:1
	v_add_f32_e32 v107, v104, v105
	v_add_f32_e32 v106, v102, v103
	ds_read_b128 v[108:111], v79 offset:2944
	v_add_f32_dpp v18, v18, v18 row_mirror row_mask:0xf bank_mask:0xf bound_ctrl:1
	v_fma_f32 v112, -v18, v107, v106
	v_pk_fma_f32 v[84:85], v[28:29], v[18:19], v[16:17] op_sel_hi:[1,0,1] neg_lo:[1,0,0] neg_hi:[1,0,0]
	v_pk_fma_f32 v[82:83], v[26:27], v[18:19], v[14:15] op_sel_hi:[1,0,1] neg_lo:[1,0,0] neg_hi:[1,0,0]
	v_pk_mul_f32 v[14:15], v[36:37], v[84:85]
	s_waitcnt lgkmcnt(5)
	v_pk_mul_f32 v[36:37], v[40:41], v[84:85]
	v_pk_fma_f32 v[14:15], v[34:35], v[82:83], v[14:15]
	s_waitcnt lgkmcnt(4)
	v_add_f32_e32 v81, v14, v15
	ds_write_b32 v99, v81
	s_waitcnt lgkmcnt(0)
	v_pk_fma_f32 v[36:37], v[52:53], v[80:81], v[36:37] op_sel_hi:[1,0,1]
	v_pk_mul_f32 v[34:35], v[38:39], v[82:83]
	s_nop 0
	v_add_f32_dpp v38, v112, v112 quad_perm:[1,0,3,2] row_mask:0xf bank_mask:0xf bound_ctrl:1
	s_waitcnt lgkmcnt(1)
	v_pk_mul_f32 v[104:105], v[108:109], v[46:47]
	v_pk_fma_f32 v[34:35], v[50:51], v[80:81], v[34:35] op_sel_hi:[1,0,1]
	s_nop 0
	v_add_f32_dpp v38, v38, v38 quad_perm:[2,3,0,1] row_mask:0xf bank_mask:0xf bound_ctrl:1
	v_pk_mul_f32 v[102:103], v[108:109], v[34:35]
	v_pk_fma_f32 v[104:105], v[110:111], v[48:49], v[104:105]
	ds_read_b128 v[14:17], v79 offset:2688
	ds_read_b128 v[18:21], v79 offset:2944
	ds_read_b128 v[22:25], v79 offset:3200
	ds_read_b128 v[26:29], v79 offset:3456
	ds_read_b128 v[30:33], v79 offset:3712
	ds_read_b32 v68, v78 offset:3968
	v_add_f32_dpp v38, v38, v38 row_half_mirror row_mask:0xf bank_mask:0xf bound_ctrl:1
	v_pk_fma_f32 v[102:103], v[110:111], v[36:37], v[102:103]
	v_add_f32_e32 v107, v104, v105
	v_add_f32_e32 v106, v102, v103
	s_nop 0
	v_add_f32_dpp v38, v38, v38 row_mirror row_mask:0xf bank_mask:0xf bound_ctrl:1
	v_fma_f32 v112, -v38, v107, v106
	v_pk_fma_f32 v[80:81], v[46:47], v[38:39], v[34:35] op_sel_hi:[1,0,1] neg_lo:[1,0,0] neg_hi:[1,0,0]
	v_pk_fma_f32 v[82:83], v[48:49], v[38:39], v[36:37] op_sel_hi:[1,0,1] neg_lo:[1,0,0] neg_hi:[1,0,0]
	s_waitcnt lgkmcnt(4)
	v_pk_mul_f32 v[34:35], v[66:67], v[82:83]
	v_pk_fma_f32 v[34:35], v[64:65], v[80:81], v[34:35]
	v_add_f32_e32 v64, v34, v35
	ds_write_b32 v99, v64 offset:1024
	v_pk_mul_f32 v[14:15], v[14:15], v[80:81]
	v_add_f32_dpp v18, v112, v112 quad_perm:[1,0,3,2] row_mask:0xf bank_mask:0xf bound_ctrl:1
	s_nop 1
	v_add_f32_dpp v18, v18, v18 quad_perm:[2,3,0,1] row_mask:0xf bank_mask:0xf bound_ctrl:1
	ds_read_b128 v[34:37], v79 offset:4032
	ds_read_b128 v[38:41], v79 offset:4288
	ds_read_b128 v[42:45], v79 offset:4544
	ds_read_b128 v[46:49], v79 offset:4800
	ds_read_b128 v[50:53], v79 offset:5056
	ds_read_b32 v0, v78 offset:5312
	v_add_f32_dpp v18, v18, v18 row_half_mirror row_mask:0xf bank_mask:0xf bound_ctrl:1
	ds_read_b128 v[108:111], v79 offset:5632
	s_waitcnt lgkmcnt(6)
	v_pk_fma_f32 v[14:15], v[26:27], v[68:69], v[14:15] op_sel_hi:[1,0,1]
	v_pk_mul_f32 v[16:17], v[16:17], v[82:83]
	v_add_f32_dpp v18, v18, v18 row_mirror row_mask:0xf bank_mask:0xf bound_ctrl:1
	v_pk_fma_f32 v[16:17], v[28:29], v[68:69], v[16:17] op_sel_hi:[1,0,1]
	v_pk_fma_f32 v[64:65], v[22:23], v[18:19], v[14:15] op_sel_hi:[1,0,1] neg_lo:[1,0,0] neg_hi:[1,0,0]
	v_pk_fma_f32 v[66:67], v[24:25], v[18:19], v[16:17] op_sel_hi:[1,0,1] neg_lo:[1,0,0] neg_hi:[1,0,0]
	s_waitcnt lgkmcnt(4)
	v_pk_mul_f32 v[38:39], v[38:39], v[64:65]
	v_pk_mul_f32 v[34:35], v[34:35], v[64:65]
	v_pk_fma_f32 v[38:39], v[40:41], v[66:67], v[38:39]
	v_pk_mul_f32 v[36:37], v[36:37], v[66:67]
	v_add_f32_e32 v38, v38, v39
	s_waitcnt lgkmcnt(0)
	v_pk_fma_f32 v[34:35], v[46:47], v[0:1], v[34:35] op_sel_hi:[1,0,1]
	v_pk_fma_f32 v[36:37], v[48:49], v[0:1], v[36:37] op_sel_hi:[1,0,1]
	v_add_f32_dpp v0, v38, v38 quad_perm:[1,0,3,2] row_mask:0xf bank_mask:0xf bound_ctrl:1
	s_waitcnt lgkmcnt(0)
; DI void scan_block(float* ldsf, const u16* __restrict__ R, const u16* __restrict__ KP, const u16* __restrict__ KK, const u16* __restrict__ KKA,
;                    const u16* __restrict__ V, const float* __restrict__ Wd, float* __restrict__ Y, int blk, int wid_k) {
;     ...
;       for (int step = 0; step < 16; ++step) {
;         float4 w4n = w4, kk4n = kk4, ka4n = ka4, kp4n = kp4, r4n = r4; float vvn = vv;
;         if (step + 1 < 16) {
;           const float* sp = bp + (step + 1) * 336;
;           w4n = *(const float4*)(sp + ks * 4);
;           kk4n = *(const float4*)(sp + 64 + ks * 4);
;           ka4n = *(const float4*)(sp + 128 + ks * 4);
;           kp4n = *(const float4*)(sp + 192 + ks * 4);
;           r4n = *(const float4*)(sp + 256 + ks * 4);
;           vvn = sp[320 + rowl];
;         }
;         const f2 kka = {kk4.x, kk4.y}, kkb = {kk4.z, kk4.w}, wa = {w4.x, w4.y}, wb = {w4.z, w4.w};
;         const f2 kaa = {ka4.x, ka4.y}, kab = {ka4.z, ka4.w}, kpa = {kp4.x, kp4.y}, kpb = {kp4.z, kp4.w};
;         const f2 ra = {r4.x, r4.y}, rb = {r4.z, r4.w};
;         const f2 d2 = Sa * kka + Sb * kkb;
;         float d = d2.x + d2.y;
;         const f2 ta = Sa * wa + kpa * vv, tb = Sb * wb + kpb * vv;
;         d = dpp_add<0xB1>(d); yp = dpp_add<0xB1>(yp);
;         d = dpp_add<0x4E>(d); yp = dpp_add<0x4E>(yp);
;         d = dpp_add<0x141>(d); yp = dpp_add<0x141>(yp);
;         d = dpp_add<0x140>(d); yp = dpp_add<0x140>(yp);
;         if (step > 0) yreg = (ks == step - 1) ? yp : yreg;
;         Sa = ta - kaa * d; Sb = tb - kab * d;
;         const f2 y2 = Sa * ra + Sb * rb;
;         yp = y2.x + y2.y;
;         w4 = w4n; kk4 = kk4n; ka4 = ka4n; kp4 = kp4n; r4 = r4n; vv = vvn;
;       }
	v_pk_mul_f32 v[104:105], v[108:109], v[42:43]
	v_pk_mul_f32 v[102:103], v[108:109], v[34:35]
	v_pk_mul_f32 v[14:15], v[32:33], v[66:67]
	s_nop 0
	v_add_f32_dpp v0, v0, v0 quad_perm:[2,3,0,1] row_mask:0xf bank_mask:0xf bound_ctrl:1
	v_pk_fma_f32 v[104:105], v[110:111], v[44:45], v[104:105]
	v_pk_fma_f32 v[102:103], v[110:111], v[36:37], v[102:103]
	v_pk_fma_f32 v[14:15], v[30:31], v[64:65], v[14:15]
	s_nop 0
	v_add_f32_dpp v0, v0, v0 row_half_mirror row_mask:0xf bank_mask:0xf bound_ctrl:1
	v_add_f32_e32 v107, v104, v105
	v_add_f32_e32 v106, v102, v103
	v_add_f32_e32 v81, v14, v15
	ds_write_b32 v99, v81 offset:2048
	ds_read_b128 v[14:17], v79 offset:5376
	ds_read_b128 v[18:21], v79 offset:5632
	ds_read_b128 v[22:25], v79 offset:5888
	ds_read_b128 v[26:29], v79 offset:6144
	ds_read_b128 v[30:33], v79 offset:6400
	ds_read_b32 v68, v78 offset:6656
	v_add_f32_dpp v0, v0, v0 row_mirror row_mask:0xf bank_mask:0xf bound_ctrl:1
	v_fma_f32 v112, -v0, v107, v106
	v_pk_fma_f32 v[64:65], v[42:43], v[0:1], v[34:35] op_sel_hi:[1,0,1] neg_lo:[1,0,0] neg_hi:[1,0,0]
	v_pk_fma_f32 v[66:67], v[44:45], v[0:1], v[36:37] op_sel_hi:[1,0,1] neg_lo:[1,0,0] neg_hi:[1,0,0]
	s_waitcnt lgkmcnt(4)
	v_pk_mul_f32 v[34:35], v[52:53], v[66:67]
	v_pk_fma_f32 v[34:35], v[50:51], v[64:65], v[34:35]
	v_add_f32_e32 v0, v34, v35
	ds_write_b32 v99, v0 offset:3072
	v_add_f32_dpp v18, v112, v112 quad_perm:[1,0,3,2] row_mask:0xf bank_mask:0xf bound_ctrl:1
	s_nop 1
	v_add_f32_dpp v18, v18, v18 quad_perm:[2,3,0,1] row_mask:0xf bank_mask:0xf bound_ctrl:1
	v_pk_mul_f32 v[14:15], v[14:15], v[64:65]
	v_pk_mul_f32 v[16:17], v[16:17], v[66:67]
	v_add_f32_dpp v18, v18, v18 row_half_mirror row_mask:0xf bank_mask:0xf bound_ctrl:1
	s_waitcnt lgkmcnt(0)
	v_pk_fma_f32 v[14:15], v[26:27], v[68:69], v[14:15] op_sel_hi:[1,0,1]
	v_pk_fma_f32 v[16:17], v[28:29], v[68:69], v[16:17] op_sel_hi:[1,0,1]
	v_add_f32_dpp v0, v18, v18 row_mirror row_mask:0xf bank_mask:0xf bound_ctrl:1
	ds_read_b128 v[34:37], v79 offset:6720
	ds_read_b128 v[38:41], v79 offset:6976
	ds_read_b128 v[42:45], v79 offset:7232
	ds_read_b128 v[46:49], v79 offset:7488
	ds_read_b128 v[50:53], v79 offset:7744
	ds_read_b32 v80, v78 offset:8000
	v_pk_fma_f32 v[64:65], v[22:23], v[0:1], v[14:15] op_sel_hi:[1,0,1] neg_lo:[1,0,0] neg_hi:[1,0,0]
	v_pk_fma_f32 v[66:67], v[24:25], v[0:1], v[16:17] op_sel_hi:[1,0,1] neg_lo:[1,0,0] neg_hi:[1,0,0]
	s_waitcnt lgkmcnt(4)
	v_pk_mul_f32 v[38:39], v[38:39], v[64:65]
	v_pk_mul_f32 v[14:15], v[32:33], v[66:67]
	v_pk_fma_f32 v[14:15], v[30:31], v[64:65], v[14:15]
	v_pk_fma_f32 v[38:39], v[40:41], v[66:67], v[38:39]
	v_add_f32_e32 v81, v14, v15
	ds_write_b32 v99, v81 offset:4096
	v_add_f32_e32 v38, v38, v39
	v_pk_mul_f32 v[34:35], v[34:35], v[64:65]
	s_nop 0
	v_add_f32_dpp v38, v38, v38 quad_perm:[1,0,3,2] row_mask:0xf bank_mask:0xf bound_ctrl:1
	ds_read_b128 v[22:25], v79 offset:8064
	ds_read_b128 v[30:33], v79 offset:8320
	ds_read_b128 v[14:17], v79 offset:8576
	ds_read_b128 v[26:29], v79 offset:8832
	ds_read_b128 v[18:21], v79 offset:9088
	ds_read_b32 v0, v78 offset:9344
	v_add_f32_dpp v38, v38, v38 quad_perm:[2,3,0,1] row_mask:0xf bank_mask:0xf bound_ctrl:1
	s_waitcnt lgkmcnt(6)
	v_pk_fma_f32 v[34:35], v[46:47], v[80:81], v[34:35] op_sel_hi:[1,0,1]
	v_add_f32_dpp v38, v38, v38 row_half_mirror row_mask:0xf bank_mask:0xf bound_ctrl:1
	ds_read_b128 v[108:111], v79 offset:9664
	v_pk_mul_f32 v[36:37], v[36:37], v[66:67]
	s_nop 0
	v_add_f32_dpp v38, v38, v38 row_mirror row_mask:0xf bank_mask:0xf bound_ctrl:1
	v_pk_fma_f32 v[36:37], v[48:49], v[80:81], v[36:37] op_sel_hi:[1,0,1]
	v_pk_fma_f32 v[66:67], v[42:43], v[38:39], v[34:35] op_sel_hi:[1,0,1] neg_lo:[1,0,0] neg_hi:[1,0,0]
	v_pk_fma_f32 v[64:65], v[44:45], v[38:39], v[36:37] op_sel_hi:[1,0,1] neg_lo:[1,0,0] neg_hi:[1,0,0]
	s_waitcnt lgkmcnt(4)
	v_pk_mul_f32 v[30:31], v[30:31], v[66:67]
	v_pk_mul_f32 v[22:23], v[22:23], v[66:67]
	v_pk_fma_f32 v[30:31], v[32:33], v[64:65], v[30:31]
	v_pk_mul_f32 v[24:25], v[24:25], v[64:65]
	v_add_f32_e32 v30, v30, v31
	s_waitcnt lgkmcnt(0)
	v_pk_fma_f32 v[22:23], v[26:27], v[0:1], v[22:23] op_sel_hi:[1,0,1]
	v_pk_fma_f32 v[24:25], v[28:29], v[0:1], v[24:25] op_sel_hi:[1,0,1]
	v_add_f32_dpp v0, v30, v30 quad_perm:[1,0,3,2] row_mask:0xf bank_mask:0xf bound_ctrl:1
	s_waitcnt lgkmcnt(0)
	v_pk_mul_f32 v[104:105], v[108:109], v[14:15]
	v_pk_mul_f32 v[102:103], v[108:109], v[22:23]
	v_pk_mul_f32 v[34:35], v[52:53], v[64:65]
	s_nop 0
	v_add_f32_dpp v0, v0, v0 quad_perm:[2,3,0,1] row_mask:0xf bank_mask:0xf bound_ctrl:1
	v_pk_fma_f32 v[104:105], v[110:111], v[16:17], v[104:105]
	v_pk_fma_f32 v[102:103], v[110:111], v[24:25], v[102:103]
	v_pk_fma_f32 v[34:35], v[50:51], v[66:67], v[34:35]
	s_nop 0
	v_add_f32_dpp v0, v0, v0 row_half_mirror row_mask:0xf bank_mask:0xf bound_ctrl:1
	v_add_f32_e32 v107, v104, v105
	v_add_f32_e32 v106, v102, v103
	v_add_f32_e32 v81, v34, v35
	ds_write_b32 v99, v81 offset:5120
	ds_read_b128 v[42:45], v79 offset:9408
	ds_read_b128 v[50:53], v79 offset:9664
	ds_read_b128 v[34:37], v79 offset:9920
	ds_read_b128 v[46:49], v79 offset:10176
	ds_read_b128 v[38:41], v79 offset:10432
	ds_read_b32 v68, v78 offset:10688
	v_add_f32_dpp v0, v0, v0 row_mirror row_mask:0xf bank_mask:0xf bound_ctrl:1
	v_fma_f32 v112, -v0, v107, v106
	v_pk_fma_f32 v[64:65], v[14:15], v[0:1], v[22:23] op_sel_hi:[1,0,1] neg_lo:[1,0,0] neg_hi:[1,0,0]
	v_pk_fma_f32 v[66:67], v[16:17], v[0:1], v[24:25] op_sel_hi:[1,0,1] neg_lo:[1,0,0] neg_hi:[1,0,0]
	s_waitcnt lgkmcnt(4)
	v_pk_mul_f32 v[14:15], v[20:21], v[66:67]
	v_pk_fma_f32 v[14:15], v[18:19], v[64:65], v[14:15]
	v_add_f32_e32 v81, v14, v15
	ds_write_b32 v99, v81 offset:6144
	v_pk_mul_f32 v[42:43], v[42:43], v[64:65]
	s_waitcnt lgkmcnt(0)
; DI void scan_block(float* ldsf, const u16* __restrict__ R, const u16* __restrict__ KP, const u16* __restrict__ KK, const u16* __restrict__ KKA,
;                    const u16* __restrict__ V, const float* __restrict__ Wd, float* __restrict__ Y, int blk, int wid_k) {
;     ...
;       for (int step = 0; step < 16; ++step) {
;         float4 w4n = w4, kk4n = kk4, ka4n = ka4, kp4n = kp4, r4n = r4; float vvn = vv;
;         if (step + 1 < 16) {
;           const float* sp = bp + (step + 1) * 336;
;           w4n = *(const float4*)(sp + ks * 4);
;           kk4n = *(const float4*)(sp + 64 + ks * 4);
;           ka4n = *(const float4*)(sp + 128 + ks * 4);
;           kp4n = *(const float4*)(sp + 192 + ks * 4);
;           r4n = *(const float4*)(sp + 256 + ks * 4);
;           vvn = sp[320 + rowl];
;         }
;         const f2 kka = {kk4.x, kk4.y}, kkb = {kk4.z, kk4.w}, wa = {w4.x, w4.y}, wb = {w4.z, w4.w};
;         const f2 kaa = {ka4.x, ka4.y}, kab = {ka4.z, ka4.w}, kpa = {kp4.x, kp4.y}, kpb = {kp4.z, kp4.w};
;         const f2 ra = {r4.x, r4.y}, rb = {r4.z, r4.w};
;         const f2 d2 = Sa * kka + Sb * kkb;
;         float d = d2.x + d2.y;
;         const f2 ta = Sa * wa + kpa * vv, tb = Sb * wb + kpb * vv;
;         d = dpp_add<0xB1>(d); yp = dpp_add<0xB1>(yp);
;         d = dpp_add<0x4E>(d); yp = dpp_add<0x4E>(yp);
;         d = dpp_add<0x141>(d); yp = dpp_add<0x141>(yp);
;         d = dpp_add<0x140>(d); yp = dpp_add<0x140>(yp);
;         if (step > 0) yreg = (ks == step - 1) ? yp : yreg;
;         Sa = ta - kaa * d; Sb = tb - kab * d;
;         const f2 y2 = Sa * ra + Sb * rb;
;         yp = y2.x + y2.y;
;         w4 = w4n; kk4 = kk4n; ka4 = ka4n; kp4 = kp4n; r4 = r4n; vv = vvn;
;       }
	v_pk_fma_f32 v[42:43], v[46:47], v[68:69], v[42:43] op_sel_hi:[1,0,1]
	v_add_f32_dpp v46, v112, v112 quad_perm:[1,0,3,2] row_mask:0xf bank_mask:0xf bound_ctrl:1
	s_nop 1
	v_add_f32_dpp v46, v46, v46 quad_perm:[2,3,0,1] row_mask:0xf bank_mask:0xf bound_ctrl:1
	s_nop 1
	v_add_f32_dpp v46, v46, v46 row_half_mirror row_mask:0xf bank_mask:0xf bound_ctrl:1
	ds_read_b128 v[108:111], v79 offset:12352
	ds_read_b128 v[14:17], v79 offset:10752
	ds_read_b128 v[18:21], v79 offset:11008
	ds_read_b128 v[22:25], v79 offset:11264
	ds_read_b128 v[26:29], v79 offset:11520
	ds_read_b128 v[30:33], v79 offset:11776
	ds_read_b32 v0, v78 offset:12032
	v_pk_mul_f32 v[44:45], v[44:45], v[66:67]
	v_add_f32_dpp v46, v46, v46 row_mirror row_mask:0xf bank_mask:0xf bound_ctrl:1
	v_pk_fma_f32 v[44:45], v[48:49], v[68:69], v[44:45] op_sel_hi:[1,0,1]
	v_pk_fma_f32 v[64:65], v[34:35], v[46:47], v[42:43] op_sel_hi:[1,0,1] neg_lo:[1,0,0] neg_hi:[1,0,0]
	v_pk_fma_f32 v[66:67], v[36:37], v[46:47], v[44:45] op_sel_hi:[1,0,1] neg_lo:[1,0,0] neg_hi:[1,0,0]
	s_waitcnt lgkmcnt(4)
	v_pk_mul_f32 v[18:19], v[18:19], v[64:65]
	v_pk_mul_f32 v[14:15], v[14:15], v[64:65]
	v_pk_fma_f32 v[18:19], v[20:21], v[66:67], v[18:19]
	v_pk_mul_f32 v[16:17], v[16:17], v[66:67]
	v_add_f32_e32 v18, v18, v19
	s_waitcnt lgkmcnt(0)
	v_pk_fma_f32 v[14:15], v[26:27], v[0:1], v[14:15] op_sel_hi:[1,0,1]
	v_pk_fma_f32 v[16:17], v[28:29], v[0:1], v[16:17] op_sel_hi:[1,0,1]
	v_add_f32_dpp v0, v18, v18 quad_perm:[1,0,3,2] row_mask:0xf bank_mask:0xf bound_ctrl:1
	s_waitcnt lgkmcnt(6)
	v_pk_mul_f32 v[104:105], v[108:109], v[22:23]
	v_pk_mul_f32 v[102:103], v[108:109], v[14:15]
	v_pk_mul_f32 v[34:35], v[40:41], v[66:67]
	s_nop 0
	v_add_f32_dpp v0, v0, v0 quad_perm:[2,3,0,1] row_mask:0xf bank_mask:0xf bound_ctrl:1
	v_pk_fma_f32 v[104:105], v[110:111], v[24:25], v[104:105]
	v_pk_fma_f32 v[102:103], v[110:111], v[16:17], v[102:103]
	v_pk_fma_f32 v[34:35], v[38:39], v[64:65], v[34:35]
	s_nop 0
	v_add_f32_dpp v0, v0, v0 row_half_mirror row_mask:0xf bank_mask:0xf bound_ctrl:1
	v_add_f32_e32 v107, v104, v105
	v_add_f32_e32 v106, v102, v103
	v_add_f32_e32 v81, v34, v35
	ds_write_b32 v99, v81 offset:7168
	ds_read_b128 v[34:37], v79 offset:12096
	ds_read_b128 v[38:41], v79 offset:12352
	ds_read_b128 v[42:45], v79 offset:12608
	ds_read_b128 v[46:49], v79 offset:12864
	ds_read_b128 v[50:53], v79 offset:13120
	ds_read_b32 v68, v78 offset:13376
	v_add_f32_dpp v0, v0, v0 row_mirror row_mask:0xf bank_mask:0xf bound_ctrl:1
	v_fma_f32 v112, -v0, v107, v106
	v_pk_fma_f32 v[64:65], v[22:23], v[0:1], v[14:15] op_sel_hi:[1,0,1] neg_lo:[1,0,0] neg_hi:[1,0,0]
	v_pk_fma_f32 v[66:67], v[24:25], v[0:1], v[16:17] op_sel_hi:[1,0,1] neg_lo:[1,0,0] neg_hi:[1,0,0]
	s_waitcnt lgkmcnt(4)
	v_pk_mul_f32 v[14:15], v[32:33], v[66:67]
	v_pk_fma_f32 v[14:15], v[30:31], v[64:65], v[14:15]
	v_add_f32_e32 v81, v14, v15
	ds_write_b32 v99, v81 offset:8192
	s_nop 1
	v_add_f32_dpp v38, v112, v112 quad_perm:[1,0,3,2] row_mask:0xf bank_mask:0xf bound_ctrl:1
	s_nop 1
	v_add_f32_dpp v38, v38, v38 quad_perm:[2,3,0,1] row_mask:0xf bank_mask:0xf bound_ctrl:1
	v_pk_mul_f32 v[34:35], v[34:35], v[64:65]
	s_nop 0
	v_add_f32_dpp v38, v38, v38 row_half_mirror row_mask:0xf bank_mask:0xf bound_ctrl:1
	ds_read_b128 v[108:111], v79 offset:15040
	ds_read_b128 v[14:17], v79 offset:13440
	ds_read_b128 v[18:21], v79 offset:13696
	ds_read_b128 v[22:25], v79 offset:13952
	ds_read_b128 v[26:29], v79 offset:14208
	ds_read_b128 v[30:33], v79 offset:14464
	ds_read_b32 v0, v78 offset:14720
	s_waitcnt lgkmcnt(6)
	v_pk_fma_f32 v[34:35], v[46:47], v[68:69], v[34:35] op_sel_hi:[1,0,1]
	v_pk_mul_f32 v[36:37], v[36:37], v[66:67]
	v_add_f32_dpp v38, v38, v38 row_mirror row_mask:0xf bank_mask:0xf bound_ctrl:1
	v_pk_fma_f32 v[36:37], v[48:49], v[68:69], v[36:37] op_sel_hi:[1,0,1]
	v_pk_fma_f32 v[64:65], v[42:43], v[38:39], v[34:35] op_sel_hi:[1,0,1] neg_lo:[1,0,0] neg_hi:[1,0,0]
	v_pk_fma_f32 v[66:67], v[44:45], v[38:39], v[36:37] op_sel_hi:[1,0,1] neg_lo:[1,0,0] neg_hi:[1,0,0]
	s_waitcnt lgkmcnt(4)
	v_pk_mul_f32 v[18:19], v[18:19], v[64:65]
	v_pk_mul_f32 v[14:15], v[14:15], v[64:65]
	v_pk_fma_f32 v[18:19], v[20:21], v[66:67], v[18:19]
	v_pk_mul_f32 v[16:17], v[16:17], v[66:67]
	v_add_f32_e32 v18, v18, v19
	s_waitcnt lgkmcnt(0)
	v_pk_fma_f32 v[14:15], v[26:27], v[0:1], v[14:15] op_sel_hi:[1,0,1]
	v_pk_fma_f32 v[16:17], v[28:29], v[0:1], v[16:17] op_sel_hi:[1,0,1]
	v_add_f32_dpp v0, v18, v18 quad_perm:[1,0,3,2] row_mask:0xf bank_mask:0xf bound_ctrl:1
	s_waitcnt lgkmcnt(6)
	v_pk_mul_f32 v[104:105], v[108:109], v[22:23]
	v_pk_mul_f32 v[102:103], v[108:109], v[14:15]
	v_pk_mul_f32 v[34:35], v[52:53], v[66:67]
	s_nop 0
	v_add_f32_dpp v0, v0, v0 quad_perm:[2,3,0,1] row_mask:0xf bank_mask:0xf bound_ctrl:1
	v_pk_fma_f32 v[104:105], v[110:111], v[24:25], v[104:105]
	v_pk_fma_f32 v[102:103], v[110:111], v[16:17], v[102:103]
	v_pk_fma_f32 v[34:35], v[50:51], v[64:65], v[34:35]
	s_nop 0
	v_add_f32_dpp v0, v0, v0 row_half_mirror row_mask:0xf bank_mask:0xf bound_ctrl:1
	v_add_f32_e32 v107, v104, v105
	v_add_f32_e32 v106, v102, v103
	v_add_f32_e32 v81, v34, v35
	ds_write_b32 v99, v81 offset:9216
	ds_read_b128 v[34:37], v79 offset:14784
	ds_read_b128 v[38:41], v79 offset:15040
	ds_read_b128 v[42:45], v79 offset:15296
	ds_read_b128 v[46:49], v79 offset:15552
	ds_read_b128 v[50:53], v79 offset:15808
	ds_read_b32 v68, v78 offset:16064
	v_add_f32_dpp v0, v0, v0 row_mirror row_mask:0xf bank_mask:0xf bound_ctrl:1
	v_fma_f32 v112, -v0, v107, v106
	v_pk_fma_f32 v[64:65], v[22:23], v[0:1], v[14:15] op_sel_hi:[1,0,1] neg_lo:[1,0,0] neg_hi:[1,0,0]
	v_pk_fma_f32 v[66:67], v[24:25], v[0:1], v[16:17] op_sel_hi:[1,0,1] neg_lo:[1,0,0] neg_hi:[1,0,0]
	s_waitcnt lgkmcnt(4)
; DI void scan_block(float* ldsf, const u16* __restrict__ R, const u16* __restrict__ KP, const u16* __restrict__ KK, const u16* __restrict__ KKA,
;                    const u16* __restrict__ V, const float* __restrict__ Wd, float* __restrict__ Y, int blk, int wid_k) {
;     ...
;       for (int step = 0; step < 16; ++step) {
;         float4 w4n = w4, kk4n = kk4, ka4n = ka4, kp4n = kp4, r4n = r4; float vvn = vv;
;         if (step + 1 < 16) {
;           const float* sp = bp + (step + 1) * 336;
;           w4n = *(const float4*)(sp + ks * 4);
;           kk4n = *(const float4*)(sp + 64 + ks * 4);
;           ka4n = *(const float4*)(sp + 128 + ks * 4);
;           kp4n = *(const float4*)(sp + 192 + ks * 4);
;           r4n = *(const float4*)(sp + 256 + ks * 4);
;           vvn = sp[320 + rowl];
;         }
;         const f2 kka = {kk4.x, kk4.y}, kkb = {kk4.z, kk4.w}, wa = {w4.x, w4.y}, wb = {w4.z, w4.w};
;         const f2 kaa = {ka4.x, ka4.y}, kab = {ka4.z, ka4.w}, kpa = {kp4.x, kp4.y}, kpb = {kp4.z, kp4.w};
;         const f2 ra = {r4.x, r4.y}, rb = {r4.z, r4.w};
;         const f2 d2 = Sa * kka + Sb * kkb;
;         float d = d2.x + d2.y;
;         const f2 ta = Sa * wa + kpa * vv, tb = Sb * wb + kpb * vv;
;         d = dpp_add<0xB1>(d); yp = dpp_add<0xB1>(yp);
;         d = dpp_add<0x4E>(d); yp = dpp_add<0x4E>(yp);
;         d = dpp_add<0x141>(d); yp = dpp_add<0x141>(yp);
;         d = dpp_add<0x140>(d); yp = dpp_add<0x140>(yp);
;         if (step > 0) yreg = (ks == step - 1) ? yp : yreg;
;         Sa = ta - kaa * d; Sb = tb - kab * d;
;         const f2 y2 = Sa * ra + Sb * rb;
;         yp = y2.x + y2.y;
;         w4 = w4n; kk4 = kk4n; ka4 = ka4n; kp4 = kp4n; r4 = r4n; vv = vvn;
;       }
;       yp = reduce16(yp);
;       yreg = (ks == 15) ? yp : yreg;
;       S0 = Sa.x; S1 = Sa.y; S2 = Sb.x; S3 = Sb.y;
;       yb[ks * 16 + rowl] = yreg;
	v_pk_mul_f32 v[14:15], v[32:33], v[66:67]
	v_pk_fma_f32 v[14:15], v[30:31], v[64:65], v[14:15]
	v_add_f32_e32 v81, v14, v15
	ds_write_b32 v99, v81 offset:10240
	s_nop 1
	v_add_f32_dpp v38, v112, v112 quad_perm:[1,0,3,2] row_mask:0xf bank_mask:0xf bound_ctrl:1
	s_nop 1
	v_add_f32_dpp v38, v38, v38 quad_perm:[2,3,0,1] row_mask:0xf bank_mask:0xf bound_ctrl:1
	v_pk_mul_f32 v[34:35], v[34:35], v[64:65]
	s_nop 0
	v_add_f32_dpp v38, v38, v38 row_half_mirror row_mask:0xf bank_mask:0xf bound_ctrl:1
	ds_read_b128 v[108:111], v79 offset:17728
	ds_read_b128 v[14:17], v79 offset:16128
	ds_read_b128 v[18:21], v79 offset:16384
	ds_read_b128 v[22:25], v79 offset:16640
	ds_read_b128 v[26:29], v79 offset:16896
	ds_read_b128 v[30:33], v79 offset:17152
	ds_read_b32 v0, v78 offset:17408
	s_waitcnt lgkmcnt(6)
	v_pk_fma_f32 v[34:35], v[46:47], v[68:69], v[34:35] op_sel_hi:[1,0,1]
	v_pk_mul_f32 v[36:37], v[36:37], v[66:67]
	v_add_f32_dpp v38, v38, v38 row_mirror row_mask:0xf bank_mask:0xf bound_ctrl:1
	v_pk_fma_f32 v[36:37], v[48:49], v[68:69], v[36:37] op_sel_hi:[1,0,1]
	v_pk_fma_f32 v[64:65], v[42:43], v[38:39], v[34:35] op_sel_hi:[1,0,1] neg_lo:[1,0,0] neg_hi:[1,0,0]
	v_pk_fma_f32 v[66:67], v[44:45], v[38:39], v[36:37] op_sel_hi:[1,0,1] neg_lo:[1,0,0] neg_hi:[1,0,0]
	s_waitcnt lgkmcnt(4)
	v_pk_mul_f32 v[18:19], v[18:19], v[64:65]
	v_pk_mul_f32 v[14:15], v[14:15], v[64:65]
	v_pk_fma_f32 v[18:19], v[20:21], v[66:67], v[18:19]
	v_pk_mul_f32 v[16:17], v[16:17], v[66:67]
	v_add_f32_e32 v18, v18, v19
	s_waitcnt lgkmcnt(0)
	v_pk_fma_f32 v[14:15], v[26:27], v[0:1], v[14:15] op_sel_hi:[1,0,1]
	v_pk_fma_f32 v[16:17], v[28:29], v[0:1], v[16:17] op_sel_hi:[1,0,1]
	v_add_f32_dpp v0, v18, v18 quad_perm:[1,0,3,2] row_mask:0xf bank_mask:0xf bound_ctrl:1
	s_waitcnt lgkmcnt(6)
	v_pk_mul_f32 v[104:105], v[108:109], v[22:23]
	v_pk_mul_f32 v[102:103], v[108:109], v[14:15]
	v_pk_mul_f32 v[34:35], v[52:53], v[66:67]
	s_nop 0
	v_add_f32_dpp v0, v0, v0 quad_perm:[2,3,0,1] row_mask:0xf bank_mask:0xf bound_ctrl:1
	v_pk_fma_f32 v[104:105], v[110:111], v[24:25], v[104:105]
	v_pk_fma_f32 v[102:103], v[110:111], v[16:17], v[102:103]
	v_pk_fma_f32 v[34:35], v[50:51], v[64:65], v[34:35]
	s_nop 0
	v_add_f32_dpp v0, v0, v0 row_half_mirror row_mask:0xf bank_mask:0xf bound_ctrl:1
	v_add_f32_e32 v107, v104, v105
	v_add_f32_e32 v106, v102, v103
	v_add_f32_e32 v81, v34, v35
	ds_write_b32 v99, v81 offset:11264
	ds_read_b128 v[34:37], v79 offset:17472
	ds_read_b128 v[38:41], v79 offset:17728
	ds_read_b128 v[42:45], v79 offset:17984
	ds_read_b128 v[46:49], v79 offset:18240
	ds_read_b128 v[50:53], v79 offset:18496
	ds_read_b32 v68, v78 offset:18752
	v_add_f32_dpp v0, v0, v0 row_mirror row_mask:0xf bank_mask:0xf bound_ctrl:1
	v_fma_f32 v112, -v0, v107, v106
	v_pk_fma_f32 v[64:65], v[22:23], v[0:1], v[14:15] op_sel_hi:[1,0,1] neg_lo:[1,0,0] neg_hi:[1,0,0]
	v_pk_fma_f32 v[66:67], v[24:25], v[0:1], v[16:17] op_sel_hi:[1,0,1] neg_lo:[1,0,0] neg_hi:[1,0,0]
	s_waitcnt lgkmcnt(4)
	v_pk_mul_f32 v[14:15], v[32:33], v[66:67]
	v_pk_fma_f32 v[14:15], v[30:31], v[64:65], v[14:15]
	v_add_f32_e32 v81, v14, v15
	ds_write_b32 v99, v81 offset:12288
	s_nop 1
	v_add_f32_dpp v38, v112, v112 quad_perm:[1,0,3,2] row_mask:0xf bank_mask:0xf bound_ctrl:1
	s_nop 1
	v_add_f32_dpp v38, v38, v38 quad_perm:[2,3,0,1] row_mask:0xf bank_mask:0xf bound_ctrl:1
	v_pk_mul_f32 v[34:35], v[34:35], v[64:65]
	s_nop 0
	v_add_f32_dpp v38, v38, v38 row_half_mirror row_mask:0xf bank_mask:0xf bound_ctrl:1
	s_waitcnt lgkmcnt(0)
	v_pk_fma_f32 v[34:35], v[46:47], v[68:69], v[34:35] op_sel_hi:[1,0,1]
	v_pk_mul_f32 v[36:37], v[36:37], v[66:67]
	v_add_f32_dpp v38, v38, v38 row_mirror row_mask:0xf bank_mask:0xf bound_ctrl:1
	ds_read_b128 v[22:25], v79 offset:18816
	ds_read_b128 v[30:33], v79 offset:19072
	ds_read_b128 v[14:17], v79 offset:19328
	ds_read_b128 v[26:29], v79 offset:19584
	ds_read_b128 v[18:21], v79 offset:19840
	ds_read_b32 v0, v78 offset:20096
	v_pk_fma_f32 v[36:37], v[48:49], v[68:69], v[36:37] op_sel_hi:[1,0,1]
	v_pk_fma_f32 v[66:67], v[42:43], v[38:39], v[34:35] op_sel_hi:[1,0,1] neg_lo:[1,0,0] neg_hi:[1,0,0]
	v_pk_fma_f32 v[64:65], v[44:45], v[38:39], v[36:37] op_sel_hi:[1,0,1] neg_lo:[1,0,0] neg_hi:[1,0,0]
	s_waitcnt lgkmcnt(4)
	v_pk_mul_f32 v[30:31], v[30:31], v[66:67]
	v_pk_mul_f32 v[22:23], v[22:23], v[66:67]
	v_pk_fma_f32 v[30:31], v[32:33], v[64:65], v[30:31]
	v_pk_mul_f32 v[34:35], v[52:53], v[64:65]
	v_add_f32_e32 v30, v30, v31
	s_waitcnt lgkmcnt(0)
	v_pk_fma_f32 v[22:23], v[26:27], v[0:1], v[22:23] op_sel_hi:[1,0,1]
	v_pk_fma_f32 v[34:35], v[50:51], v[66:67], v[34:35]
	v_add_f32_dpp v30, v30, v30 quad_perm:[1,0,3,2] row_mask:0xf bank_mask:0xf bound_ctrl:1
	v_add_f32_e32 v81, v34, v35
	ds_write_b32 v99, v81 offset:13312
	v_add_f32_dpp v30, v30, v30 quad_perm:[2,3,0,1] row_mask:0xf bank_mask:0xf bound_ctrl:1
	ds_read_b128 v[42:45], v79 offset:20160
	ds_read_b128 v[50:53], v79 offset:20416
	ds_read_b128 v[34:37], v79 offset:20672
	ds_read_b128 v[46:49], v79 offset:20928
	ds_read_b128 v[38:41], v79 offset:21184
	ds_read_b32 v68, v78 offset:21440
	v_add_f32_dpp v30, v30, v30 row_half_mirror row_mask:0xf bank_mask:0xf bound_ctrl:1
	s_nop 0
	s_nop 0
	v_add_f32_dpp v26, v30, v30 row_mirror row_mask:0xf bank_mask:0xf bound_ctrl:1
	v_pk_fma_f32 v[14:15], v[14:15], v[26:27], v[22:23] op_sel_hi:[1,0,1] neg_lo:[1,0,0] neg_hi:[1,0,0]
	v_pk_mul_f32 v[22:23], v[24:25], v[64:65]
	v_pk_fma_f32 v[22:23], v[28:29], v[0:1], v[22:23] op_sel_hi:[1,0,1]
	s_nop 0
	v_pk_fma_f32 v[16:17], v[16:17], v[26:27], v[22:23] op_sel_hi:[1,0,1] neg_lo:[1,0,0] neg_hi:[1,0,0]
	s_nop 0
	v_pk_mul_f32 v[20:21], v[20:21], v[16:17]
	s_nop 0
	v_pk_fma_f32 v[18:19], v[18:19], v[14:15], v[20:21]
	s_nop 0
	v_add_f32_e32 v0, v18, v19
	ds_write_b32 v99, v0 offset:14336
	s_waitcnt lgkmcnt(4)
	v_pk_mul_f32 v[18:19], v[50:51], v[14:15]
	v_pk_fma_f32 v[18:19], v[52:53], v[16:17], v[18:19]
	v_pk_mul_f32 v[16:17], v[44:45], v[16:17]
	v_add_f32_e32 v18, v18, v19
	v_pk_mul_f32 v[14:15], v[42:43], v[14:15]
	s_nop 0
	v_add_f32_dpp v18, v18, v18 quad_perm:[1,0,3,2] row_mask:0xf bank_mask:0xf bound_ctrl:1
	s_waitcnt lgkmcnt(0)
	v_pk_fma_f32 v[16:17], v[48:49], v[68:69], v[16:17] op_sel_hi:[1,0,1]
	v_add_f32_dpp v18, v18, v18 quad_perm:[2,3,0,1] row_mask:0xf bank_mask:0xf bound_ctrl:1
	v_pk_fma_f32 v[14:15], v[46:47], v[68:69], v[14:15] op_sel_hi:[1,0,1]
	s_nop 0
	v_add_f32_dpp v18, v18, v18 row_half_mirror row_mask:0xf bank_mask:0xf bound_ctrl:1
	s_nop 1
	v_add_f32_dpp v0, v18, v18 row_mirror row_mask:0xf bank_mask:0xf bound_ctrl:1
	v_pk_fma_f32 v[16:17], v[36:37], v[0:1], v[16:17] op_sel_hi:[1,0,1] neg_lo:[1,0,0] neg_hi:[1,0,0]
	v_pk_fma_f32 v[14:15], v[34:35], v[0:1], v[14:15] op_sel_hi:[1,0,1] neg_lo:[1,0,0] neg_hi:[1,0,0]
	v_pk_mul_f32 v[18:19], v[40:41], v[16:17]
	s_nop 0
	v_pk_fma_f32 v[18:19], v[38:39], v[14:15], v[18:19]
	s_nop 0
	v_add_f32_e32 v0, v18, v19
	ds_write_b32 v99, v0 offset:15360
	v_add3_u32 v18, s63, v75, v76
	s_nop 0
	s_nop 1
	s_nop 1
	s_nop 1
